# attention loop: all four group-0 PV MFMAs ahead of the first QK MFMA
# baseline (speedup 1.0000x reference)
; template <int KS> __device__ __forceinline__ void pv_ks(f32x16* o, int vb, bf16x8 pa) {
;     const s16x4 l0 = tr_read<v_rd_off(0, KS, 0)>(vb), h0 = tr_read<v_rd_off(0, KS, 1)>(vb), l1 = tr_read<v_rd_off(1, KS, 0)>(vb), h1 = tr_read<v_rd_off(1, KS, 1)>(vb);
;     const s16x4 l2 = tr_read<v_rd_off(2, KS, 0)>(vb), h2 = tr_read<v_rd_off(2, KS, 1)>(vb), l3 = tr_read<v_rd_off(3, KS, 0)>(vb), h3 = tr_read<v_rd_off(3, KS, 1)>(vb);
;     ...
;     asm volatile("s_waitcnt lgkmcnt(6)" ::: "memory"); SBAR();
;     o[0] = __builtin_amdgcn_mfma_f32_32x32x16_bf16(pa, PK(l0, h0), o[0], 0, 0, 0);
;     asm volatile("s_waitcnt lgkmcnt(4)" ::: "memory"); SBAR();
;     o[1] = __builtin_amdgcn_mfma_f32_32x32x16_bf16(pa, PK(l1, h1), o[1], 0, 0, 0);
;     asm volatile("s_waitcnt lgkmcnt(2)" ::: "memory"); SBAR();
;     o[2] = __builtin_amdgcn_mfma_f32_32x32x16_bf16(pa, PK(l2, h2), o[2], 0, 0, 0);
;     asm volatile("s_waitcnt lgkmcnt(0)" ::: "memory"); SBAR();
;     o[3] = __builtin_amdgcn_mfma_f32_32x32x16_bf16(pa, PK(l3, h3), o[3], 0, 0, 0);
;     ...
; }
; __device__ __forceinline__ void pv_d0(f32x16* o, int vb, bf16x8 pa0, bf16x8 pa1, bf16x8 pa2, bf16x8 pa3) {
;     __builtin_amdgcn_s_setprio(1);
;     pv_ks<0>(o, vb, pa0); pv_ks<1>(o, vb, pa1); pv_ks<2>(o, vb, pa2); pv_ks<3>(o, vb, pa3);
;     __builtin_amdgcn_s_setprio(0);
; }
; __device__ __forceinline__ void exp_half(f32x16& p) {
; #pragma unroll
;     for (int r = 0; r < 16; ++r) p[r] = __builtin_amdgcn_exp2f(p[r]);
; }
; __device__ __forceinline__ void pack_p(const f32x16& p0, const f32x16& p1, float& l_reg, bf16x8& pa0, bf16x8& pa1, bf16x8& pa2, bf16x8& pa3) {
;     float ps = 0;
; #pragma unroll
;     for (int r = 0; r < 16; ++r) ps += p0[r];
; #pragma unroll
;     for (int r = 0; r < 16; ++r) ps += p1[r];
;     l_reg += ps;
;     ...
;     PK4(p0, 0, pa0); PK4(p0, 8, pa1); PK4(p1, 0, pa2); PK4(p1, 8, pa3);
;     ...
; }
; template <int ND0> __device__ __forceinline__ void qkt(f32x16& p0, f32x16& p1, const char* Ks, const bf16x8* qr, int r32, int hi, int colB0) {
; #pragma unroll
;     for (int d0 = 0; d0 < ND0; ++d0) { const int cb = colB0 + (d0 * 16 + hi * 8) * 2;
;         const bf16x8 b0 = *reinterpret_cast<const bf16x8*>(Ks + KSWZ(r32, cb));
;         const bf16x8 b1 = *reinterpret_cast<const bf16x8*>(Ks + KSWZ(32 + r32, cb));
;         p0 = __builtin_amdgcn_mfma_f32_32x32x16_bf16(b0, qr[d0], p0, 0, 0, 0);
.Lsym_nostage_s0:
	s_waitcnt lgkmcnt(14)
	v_mfma_f32_32x32x16_bf16 v[48:63], v[128:131], v[144:147], v[48:63]
	ds_read_b64_tr_b16 v[144:145], v252 offset:4096
	ds_read_b64_tr_b16 v[146:147], v252 offset:6144
	v_exp_f32_e32 v88, v88
	v_exp_f32_e32 v89, v89
	v_exp_f32_e32 v90, v90
	s_waitcnt lgkmcnt(14)
	v_mfma_f32_32x32x16_bf16 v[32:47], v[128:131], v[148:151], v[32:47]
	ds_read_b64_tr_b16 v[148:149], v252 offset:4608
	ds_read_b64_tr_b16 v[150:151], v252 offset:6656
	v_exp_f32_e32 v91, v91
	v_add_f32_e32 v182, v88, v182
	v_add_f32_e32 v182, v89, v182
	v_cvt_pk_bf16_f32 v132, v88, v89
	v_exp_f32_e32 v92, v92
	s_waitcnt lgkmcnt(14)
	v_mfma_f32_32x32x16_bf16 v[16:31], v[128:131], v[152:155], v[16:31]
	ds_read_b64_tr_b16 v[152:153], v252 offset:5120
	ds_read_b64_tr_b16 v[154:155], v252 offset:7168
	v_exp_f32_e32 v93, v93
	v_add_f32_e32 v182, v90, v182
	v_add_f32_e32 v182, v91, v182
	v_cvt_pk_bf16_f32 v133, v90, v91
	s_waitcnt lgkmcnt(14)
	v_mfma_f32_32x32x16_bf16 v[0:15], v[128:131], v[156:159], v[0:15]
	ds_read_b64_tr_b16 v[156:157], v252 offset:5632
	ds_read_b64_tr_b16 v[158:159], v252 offset:7680
	v_exp_f32_e32 v94, v94
	v_exp_f32_e32 v95, v95
	v_add_f32_e32 v182, v92, v182
	v_add_f32_e32 v182, v93, v182
	s_waitcnt lgkmcnt(15)
	v_mfma_f32_32x32x16_bf16 v[112:127], v[192:195], v[172:175], v[112:127]
	v_cvt_pk_bf16_f32 v134, v92, v93
	v_cvt_pk_bf16_f32 v135, v94, v95
	v_add_f32_e32 v182, v94, v182
	v_add_f32_e32 v182, v95, v182
	v_exp_f32_e32 v64, v64
	s_waitcnt lgkmcnt(6)
	v_mfma_f32_32x32x16_bf16 v[48:63], v[132:135], v[144:147], v[48:63]
	ds_read_b64_tr_b16 v[144:145], v252 offset:8192
	ds_read_b64_tr_b16 v[146:147], v252 offset:10240
	v_exp_f32_e32 v65, v65
	v_exp_f32_e32 v66, v66
	v_exp_f32_e32 v67, v67
	v_add_f32_e32 v182, v64, v182
	v_mfma_f32_32x32x16_bf16 v[96:111], v[196:199], v[172:175], v[96:111]
	v_add_f32_e32 v182, v65, v182
	v_cvt_pk_bf16_f32 v136, v64, v65
	v_exp_f32_e32 v68, v68
	v_exp_f32_e32 v69, v69
	s_waitcnt lgkmcnt(6)
	v_mfma_f32_32x32x16_bf16 v[32:47], v[132:135], v[148:151], v[32:47]
	ds_read_b64_tr_b16 v[148:149], v252 offset:8704
	ds_read_b64_tr_b16 v[150:151], v252 offset:10752
	v_add_f32_e32 v182, v66, v182
	v_add_f32_e32 v182, v67, v182
	v_cvt_pk_bf16_f32 v137, v66, v67
	v_exp_f32_e32 v70, v70
	v_mfma_f32_32x32x16_bf16 v[112:127], v[200:203], v[168:171], v[112:127]
	v_exp_f32_e32 v71, v71
	v_add_f32_e32 v182, v68, v182
	v_add_f32_e32 v182, v69, v182
	v_cvt_pk_bf16_f32 v138, v68, v69
	v_cvt_pk_bf16_f32 v139, v70, v71
	v_add_f32_e32 v182, v70, v182
	s_waitcnt lgkmcnt(6)
	v_mfma_f32_32x32x16_bf16 v[16:31], v[132:135], v[152:155], v[16:31]
	ds_read_b64_tr_b16 v[152:153], v252 offset:9216
	ds_read_b64_tr_b16 v[154:155], v252 offset:11264
	v_add_f32_e32 v182, v71, v182
	v_exp_f32_e32 v72, v72
	v_exp_f32_e32 v73, v73
	v_exp_f32_e32 v74, v74
	v_mfma_f32_32x32x16_bf16 v[96:111], v[204:207], v[168:171], v[96:111]
	v_exp_f32_e32 v75, v75
	v_add_f32_e32 v182, v72, v182
	v_add_f32_e32 v182, v73, v182
	v_cvt_pk_bf16_f32 v140, v72, v73
	s_waitcnt lgkmcnt(6)
	v_mfma_f32_32x32x16_bf16 v[0:15], v[132:135], v[156:159], v[0:15]
	ds_read_b64_tr_b16 v[156:157], v252 offset:9728
	ds_read_b64_tr_b16 v[158:159], v252 offset:11776
	v_exp_f32_e32 v76, v76
	v_exp_f32_e32 v77, v77
	v_add_f32_e32 v182, v74, v182
	v_add_f32_e32 v182, v75, v182
	v_mfma_f32_32x32x16_bf16 v[112:127], v[208:211], v[164:167], v[112:127]
	v_cvt_pk_bf16_f32 v141, v74, v75
	v_exp_f32_e32 v78, v78
	v_exp_f32_e32 v79, v79
	v_add_f32_e32 v182, v76, v182
	v_mfma_f32_32x32x16_bf16 v[96:111], v[212:215], v[164:167], v[96:111]
	v_add_f32_e32 v182, v77, v182
	v_cvt_pk_bf16_f32 v142, v76, v77
	v_cvt_pk_bf16_f32 v143, v78, v79
	v_add_f32_e32 v182, v78, v182
	v_add_f32_e32 v182, v79, v182
	s_cmp_lt_i32 s55, 0
	s_cselect_b32 s100, -1.0, 1.0
	v_mul_f32_e32 v185, s100, v186
	v_mfma_f32_32x32x16_bf16 v[112:127], v[216:219], v[160:163], v[112:127]
	v_fma_f32 v187, -v185, v183, s16
	v_fmamk_f32 v80, v185, 0x00000000, v187
	v_fmamk_f32 v81, v185, 0x3f800000, v187
	v_fmamk_f32 v82, v185, 0x40000000, v187
	v_fmamk_f32 v83, v185, 0x40400000, v187
	v_fmamk_f32 v84, v185, 0x41000000, v187
	v_mfma_f32_32x32x16_bf16 v[96:111], v[220:223], v[160:163], v[96:111]
	v_fmamk_f32 v85, v185, 0x41100000, v187
	v_fmamk_f32 v86, v185, 0x41200000, v187
	v_fmamk_f32 v87, v185, 0x41300000, v187
	v_fmamk_f32 v88, v185, 0x41800000, v187
	v_fmamk_f32 v89, v185, 0x41880000, v187
	v_fmamk_f32 v90, v185, 0x41900000, v187
	s_waitcnt lgkmcnt(6)
	v_mfma_f32_32x32x16_bf16 v[48:63], v[136:139], v[144:147], v[48:63]
	ds_read_b64_tr_b16 v[144:145], v252 offset:12288
	ds_read_b64_tr_b16 v[146:147], v252 offset:14336
	v_fmamk_f32 v91, v185, 0x41980000, v187
	v_fmamk_f32 v92, v185, 0x41c00000, v187
	v_fmamk_f32 v93, v185, 0x41c80000, v187
	v_fmamk_f32 v94, v185, 0x41d00000, v187
	v_fmamk_f32 v95, v185, 0x41d80000, v187
	v_fmamk_f32 v64, v185, 0x42000000, v187
	s_waitcnt lgkmcnt(6)
; template <int KS> __device__ __forceinline__ void pv_ks(f32x16* o, int vb, bf16x8 pa) {
;     const s16x4 l0 = tr_read<v_rd_off(0, KS, 0)>(vb), h0 = tr_read<v_rd_off(0, KS, 1)>(vb), l1 = tr_read<v_rd_off(1, KS, 0)>(vb), h1 = tr_read<v_rd_off(1, KS, 1)>(vb);
;     const s16x4 l2 = tr_read<v_rd_off(2, KS, 0)>(vb), h2 = tr_read<v_rd_off(2, KS, 1)>(vb), l3 = tr_read<v_rd_off(3, KS, 0)>(vb), h3 = tr_read<v_rd_off(3, KS, 1)>(vb);
;     ...
;     asm volatile("s_waitcnt lgkmcnt(6)" ::: "memory"); SBAR();
;     o[0] = __builtin_amdgcn_mfma_f32_32x32x16_bf16(pa, PK(l0, h0), o[0], 0, 0, 0);
;     asm volatile("s_waitcnt lgkmcnt(4)" ::: "memory"); SBAR();
;     o[1] = __builtin_amdgcn_mfma_f32_32x32x16_bf16(pa, PK(l1, h1), o[1], 0, 0, 0);
;     asm volatile("s_waitcnt lgkmcnt(2)" ::: "memory"); SBAR();
;     o[2] = __builtin_amdgcn_mfma_f32_32x32x16_bf16(pa, PK(l2, h2), o[2], 0, 0, 0);
;     asm volatile("s_waitcnt lgkmcnt(0)" ::: "memory"); SBAR();
;     o[3] = __builtin_amdgcn_mfma_f32_32x32x16_bf16(pa, PK(l3, h3), o[3], 0, 0, 0);
;     ...
; }
; __device__ __forceinline__ void pv_d0(f32x16* o, int vb, bf16x8 pa0, bf16x8 pa1, bf16x8 pa2, bf16x8 pa3) {
;     __builtin_amdgcn_s_setprio(1);
;     pv_ks<0>(o, vb, pa0); pv_ks<1>(o, vb, pa1); pv_ks<2>(o, vb, pa2); pv_ks<3>(o, vb, pa3);
;     __builtin_amdgcn_s_setprio(0);
; }
; __device__ __forceinline__ void exp_half(f32x16& p) {
; #pragma unroll
;     for (int r = 0; r < 16; ++r) p[r] = __builtin_amdgcn_exp2f(p[r]);
; }
; __device__ __forceinline__ void pack_p(const f32x16& p0, const f32x16& p1, float& l_reg, bf16x8& pa0, bf16x8& pa1, bf16x8& pa2, bf16x8& pa3) {
;     float ps = 0;
; #pragma unroll
;     for (int r = 0; r < 16; ++r) ps += p0[r];
; #pragma unroll
;     for (int r = 0; r < 16; ++r) ps += p1[r];
;     l_reg += ps;
;     ...
;     PK4(p0, 0, pa0); PK4(p0, 8, pa1); PK4(p1, 0, pa2); PK4(p1, 8, pa3);
;     ...
; }
; template <int ND0> __device__ __forceinline__ void qkt(f32x16& p0, f32x16& p1, const char* Ks, const bf16x8* qr, int r32, int hi, int colB0) {
; #pragma unroll
;     for (int d0 = 0; d0 < ND0; ++d0) { const int cb = colB0 + (d0 * 16 + hi * 8) * 2;
;         const bf16x8 b0 = *reinterpret_cast<const bf16x8*>(Ks + KSWZ(r32, cb));
;         const bf16x8 b1 = *reinterpret_cast<const bf16x8*>(Ks + KSWZ(32 + r32, cb));
;         p0 = __builtin_amdgcn_mfma_f32_32x32x16_bf16(b0, qr[d0], p0, 0, 0, 0);
	v_mfma_f32_32x32x16_bf16 v[32:47], v[136:139], v[148:151], v[32:47]
	ds_read_b64_tr_b16 v[148:149], v252 offset:12800
	ds_read_b64_tr_b16 v[150:151], v252 offset:14848
	v_fmamk_f32 v65, v185, 0x42040000, v187
	v_fmamk_f32 v66, v185, 0x42080000, v187
	v_fmamk_f32 v67, v185, 0x420c0000, v187
	v_fmamk_f32 v68, v185, 0x42200000, v187
	v_fmamk_f32 v69, v185, 0x42240000, v187
	v_fmamk_f32 v70, v185, 0x42280000, v187
	s_waitcnt lgkmcnt(6)
	v_mfma_f32_32x32x16_bf16 v[16:31], v[136:139], v[152:155], v[16:31]
	ds_read_b64_tr_b16 v[152:153], v252 offset:13312
	ds_read_b64_tr_b16 v[154:155], v252 offset:15360
	v_fmamk_f32 v71, v185, 0x422c0000, v187
	v_fmamk_f32 v72, v185, 0x42400000, v187
	v_fmamk_f32 v73, v185, 0x42440000, v187
	v_fmamk_f32 v74, v185, 0x42480000, v187
	v_fmamk_f32 v75, v185, 0x424c0000, v187
	v_fmamk_f32 v76, v185, 0x42600000, v187
	s_waitcnt lgkmcnt(6)
	v_mfma_f32_32x32x16_bf16 v[0:15], v[136:139], v[156:159], v[0:15]
	ds_read_b64_tr_b16 v[156:157], v252 offset:13824
	ds_read_b64_tr_b16 v[158:159], v252 offset:15872
	v_fmamk_f32 v77, v185, 0x42640000, v187
	v_fmamk_f32 v78, v185, 0x42680000, v187
	v_fmamk_f32 v79, v185, 0x426c0000, v187
	v_exp_f32_e32 v112, v112
	v_exp_f32_e32 v113, v113
	s_waitcnt lgkmcnt(6)
	v_mfma_f32_32x32x16_bf16 v[48:63], v[140:143], v[144:147], v[48:63]
	ds_read_b64_tr_b16 v[144:145], v252 offset:16384
	ds_read_b64_tr_b16 v[146:147], v252 offset:18432
	v_exp_f32_e32 v114, v114
	v_exp_f32_e32 v115, v115
	v_add_f32_e32 v182, v112, v182
	v_add_f32_e32 v182, v113, v182
	s_waitcnt lgkmcnt(6)
	v_mfma_f32_32x32x16_bf16 v[32:47], v[140:143], v[148:151], v[32:47]
	ds_read_b64_tr_b16 v[148:149], v252 offset:16896
	ds_read_b64_tr_b16 v[150:151], v252 offset:18944
	v_cvt_pk_bf16_f32 v128, v112, v113
	v_exp_f32_e32 v116, v116
	v_exp_f32_e32 v117, v117
	v_add_f32_e32 v182, v114, v182
	s_waitcnt lgkmcnt(6)
	v_mfma_f32_32x32x16_bf16 v[16:31], v[140:143], v[152:155], v[16:31]
	ds_read_b64_tr_b16 v[152:153], v252 offset:17408
	ds_read_b64_tr_b16 v[154:155], v252 offset:19456
	v_add_f32_e32 v182, v115, v182
	v_cvt_pk_bf16_f32 v129, v114, v115
	v_exp_f32_e32 v118, v118
	v_exp_f32_e32 v119, v119
	s_waitcnt lgkmcnt(6)
	v_mfma_f32_32x32x16_bf16 v[0:15], v[140:143], v[156:159], v[0:15]
	ds_read_b64_tr_b16 v[156:157], v252 offset:17920
	ds_read_b64_tr_b16 v[158:159], v252 offset:19968
	v_add_f32_e32 v182, v116, v182
	v_add_f32_e32 v182, v117, v182
	v_cvt_pk_bf16_f32 v130, v116, v117
	v_cvt_pk_bf16_f32 v131, v118, v119
	v_add_f32_e32 v182, v118, v182
	v_add_f32_e32 v182, v119, v182
	s_add_i32 s100, s55, 62
	s_cmp_lt_u32 s100, 93
	s_cbranch_scc0 .Lsym_nodiag_s0
	v_add_f32_e32 v190, 0x00000000, v183
	v_add_f32_e32 v191, 0xc2000000, v183
	v_fma_f32 v80, |v190|, v186, s16
	v_fma_f32 v64, |v191|, v186, s16
	v_add_f32_e32 v190, 0xbf800000, v183
	v_add_f32_e32 v191, 0xc2040000, v183
	v_fma_f32 v81, |v190|, v186, s16
	v_fma_f32 v65, |v191|, v186, s16
	v_add_f32_e32 v190, 0xc0000000, v183
	v_add_f32_e32 v191, 0xc2080000, v183
	v_fma_f32 v82, |v190|, v186, s16
	v_fma_f32 v66, |v191|, v186, s16
	v_add_f32_e32 v190, 0xc0400000, v183
	v_add_f32_e32 v191, 0xc20c0000, v183
	v_fma_f32 v83, |v190|, v186, s16
	v_fma_f32 v67, |v191|, v186, s16
	v_add_f32_e32 v190, 0xc1000000, v183
	v_add_f32_e32 v191, 0xc2200000, v183
	v_fma_f32 v84, |v190|, v186, s16
	v_fma_f32 v68, |v191|, v186, s16
	v_add_f32_e32 v190, 0xc1100000, v183
	v_add_f32_e32 v191, 0xc2240000, v183
	v_fma_f32 v85, |v190|, v186, s16
	v_fma_f32 v69, |v191|, v186, s16
	v_add_f32_e32 v190, 0xc1200000, v183
	v_add_f32_e32 v191, 0xc2280000, v183
	v_fma_f32 v86, |v190|, v186, s16
	v_fma_f32 v70, |v191|, v186, s16
	v_add_f32_e32 v190, 0xc1300000, v183
	v_add_f32_e32 v191, 0xc22c0000, v183
	v_fma_f32 v87, |v190|, v186, s16
	v_fma_f32 v71, |v191|, v186, s16
	v_add_f32_e32 v190, 0xc1800000, v183
	v_add_f32_e32 v191, 0xc2400000, v183
	v_fma_f32 v88, |v190|, v186, s16
	v_fma_f32 v72, |v191|, v186, s16
	v_add_f32_e32 v190, 0xc1880000, v183
	v_add_f32_e32 v191, 0xc2440000, v183
	v_fma_f32 v89, |v190|, v186, s16
	v_fma_f32 v73, |v191|, v186, s16
	v_add_f32_e32 v190, 0xc1900000, v183
	v_add_f32_e32 v191, 0xc2480000, v183
	v_fma_f32 v90, |v190|, v186, s16
	v_fma_f32 v74, |v191|, v186, s16
	v_add_f32_e32 v190, 0xc1980000, v183
	v_add_f32_e32 v191, 0xc24c0000, v183
	v_fma_f32 v91, |v190|, v186, s16
	v_fma_f32 v75, |v191|, v186, s16
	v_add_f32_e32 v190, 0xc1c00000, v183
	v_add_f32_e32 v191, 0xc2600000, v183
	v_fma_f32 v92, |v190|, v186, s16
	v_fma_f32 v76, |v191|, v186, s16
	v_add_f32_e32 v190, 0xc1c80000, v183
	v_add_f32_e32 v191, 0xc2640000, v183
	v_fma_f32 v93, |v190|, v186, s16
	v_fma_f32 v77, |v191|, v186, s16
	v_add_f32_e32 v190, 0xc1d00000, v183
	v_add_f32_e32 v191, 0xc2680000, v183
	v_fma_f32 v94, |v190|, v186, s16
	v_fma_f32 v78, |v191|, v186, s16
	v_add_f32_e32 v190, 0xc1d80000, v183
	v_add_f32_e32 v191, 0xc26c0000, v183
	v_fma_f32 v95, |v190|, v186, s16
	v_fma_f32 v79, |v191|, v186, s16

; template <int KS> __device__ __forceinline__ void pv_ks(f32x16* o, int vb, bf16x8 pa) {
;     const s16x4 l0 = tr_read<v_rd_off(0, KS, 0)>(vb), h0 = tr_read<v_rd_off(0, KS, 1)>(vb), l1 = tr_read<v_rd_off(1, KS, 0)>(vb), h1 = tr_read<v_rd_off(1, KS, 1)>(vb);
;     const s16x4 l2 = tr_read<v_rd_off(2, KS, 0)>(vb), h2 = tr_read<v_rd_off(2, KS, 1)>(vb), l3 = tr_read<v_rd_off(3, KS, 0)>(vb), h3 = tr_read<v_rd_off(3, KS, 1)>(vb);
;     ...
;     asm volatile("s_waitcnt lgkmcnt(6)" ::: "memory"); SBAR();
;     o[0] = __builtin_amdgcn_mfma_f32_32x32x16_bf16(pa, PK(l0, h0), o[0], 0, 0, 0);
;     asm volatile("s_waitcnt lgkmcnt(4)" ::: "memory"); SBAR();
;     o[1] = __builtin_amdgcn_mfma_f32_32x32x16_bf16(pa, PK(l1, h1), o[1], 0, 0, 0);
;     asm volatile("s_waitcnt lgkmcnt(2)" ::: "memory"); SBAR();
;     o[2] = __builtin_amdgcn_mfma_f32_32x32x16_bf16(pa, PK(l2, h2), o[2], 0, 0, 0);
;     asm volatile("s_waitcnt lgkmcnt(0)" ::: "memory"); SBAR();
;     o[3] = __builtin_amdgcn_mfma_f32_32x32x16_bf16(pa, PK(l3, h3), o[3], 0, 0, 0);
;     ...
; }
; __device__ __forceinline__ void pv_d0(f32x16* o, int vb, bf16x8 pa0, bf16x8 pa1, bf16x8 pa2, bf16x8 pa3) {
;     __builtin_amdgcn_s_setprio(1);
;     pv_ks<0>(o, vb, pa0); pv_ks<1>(o, vb, pa1); pv_ks<2>(o, vb, pa2); pv_ks<3>(o, vb, pa3);
;     __builtin_amdgcn_s_setprio(0);
; }
; __device__ __forceinline__ void exp_half(f32x16& p) {
; #pragma unroll
;     for (int r = 0; r < 16; ++r) p[r] = __builtin_amdgcn_exp2f(p[r]);
; }
; __device__ __forceinline__ void pack_p(const f32x16& p0, const f32x16& p1, float& l_reg, bf16x8& pa0, bf16x8& pa1, bf16x8& pa2, bf16x8& pa3) {
;     float ps = 0;
; #pragma unroll
;     for (int r = 0; r < 16; ++r) ps += p0[r];
; #pragma unroll
;     for (int r = 0; r < 16; ++r) ps += p1[r];
;     l_reg += ps;
;     ...
;     PK4(p0, 0, pa0); PK4(p0, 8, pa1); PK4(p1, 0, pa2); PK4(p1, 8, pa3);
;     ...
; }
; template <int ND0> __device__ __forceinline__ void qkt(f32x16& p0, f32x16& p1, const char* Ks, const bf16x8* qr, int r32, int hi, int colB0) {
; #pragma unroll
;     for (int d0 = 0; d0 < ND0; ++d0) { const int cb = colB0 + (d0 * 16 + hi * 8) * 2;
;         const bf16x8 b0 = *reinterpret_cast<const bf16x8*>(Ks + KSWZ(r32, cb));
;         const bf16x8 b1 = *reinterpret_cast<const bf16x8*>(Ks + KSWZ(32 + r32, cb));
;         p0 = __builtin_amdgcn_mfma_f32_32x32x16_bf16(b0, qr[d0], p0, 0, 0, 0);
.Lsym_nostage_s1:
	s_waitcnt lgkmcnt(14)
	v_mfma_f32_32x32x16_bf16 v[48:63], v[128:131], v[144:147], v[48:63]
	ds_read_b64_tr_b16 v[144:145], v252 offset:20480
	ds_read_b64_tr_b16 v[146:147], v252 offset:22528
	v_exp_f32_e32 v120, v120
	v_exp_f32_e32 v121, v121
	v_exp_f32_e32 v122, v122
	s_waitcnt lgkmcnt(14)
	v_mfma_f32_32x32x16_bf16 v[32:47], v[128:131], v[148:151], v[32:47]
	ds_read_b64_tr_b16 v[148:149], v252 offset:20992
	ds_read_b64_tr_b16 v[150:151], v252 offset:23040
	v_exp_f32_e32 v123, v123
	v_add_f32_e32 v182, v120, v182
	v_add_f32_e32 v182, v121, v182
	v_cvt_pk_bf16_f32 v132, v120, v121
	v_exp_f32_e32 v124, v124
	s_waitcnt lgkmcnt(14)
	v_mfma_f32_32x32x16_bf16 v[16:31], v[128:131], v[152:155], v[16:31]
	ds_read_b64_tr_b16 v[152:153], v252 offset:21504
	ds_read_b64_tr_b16 v[154:155], v252 offset:23552
	v_exp_f32_e32 v125, v125
	v_add_f32_e32 v182, v122, v182
	v_add_f32_e32 v182, v123, v182
	v_cvt_pk_bf16_f32 v133, v122, v123
	s_waitcnt lgkmcnt(14)
	v_mfma_f32_32x32x16_bf16 v[0:15], v[128:131], v[156:159], v[0:15]
	ds_read_b64_tr_b16 v[156:157], v252 offset:22016
	ds_read_b64_tr_b16 v[158:159], v252 offset:24064
	v_exp_f32_e32 v126, v126
	v_exp_f32_e32 v127, v127
	v_add_f32_e32 v182, v124, v182
	v_add_f32_e32 v182, v125, v182
	s_waitcnt lgkmcnt(15)
	v_mfma_f32_32x32x16_bf16 v[80:95], v[192:195], v[172:175], v[80:95]
	v_cvt_pk_bf16_f32 v134, v124, v125
	v_cvt_pk_bf16_f32 v135, v126, v127
	v_add_f32_e32 v182, v126, v182
	v_add_f32_e32 v182, v127, v182
	v_exp_f32_e32 v96, v96
	s_waitcnt lgkmcnt(6)
	v_mfma_f32_32x32x16_bf16 v[48:63], v[132:135], v[144:147], v[48:63]
	ds_read_b64_tr_b16 v[144:145], v252 offset:24576
	ds_read_b64_tr_b16 v[146:147], v252 offset:26624
	v_exp_f32_e32 v97, v97
	v_exp_f32_e32 v98, v98
	v_exp_f32_e32 v99, v99
	v_add_f32_e32 v182, v96, v182
	v_mfma_f32_32x32x16_bf16 v[64:79], v[196:199], v[172:175], v[64:79]
	v_add_f32_e32 v182, v97, v182
	v_cvt_pk_bf16_f32 v136, v96, v97
	v_exp_f32_e32 v100, v100
	v_exp_f32_e32 v101, v101
	s_waitcnt lgkmcnt(6)
	v_mfma_f32_32x32x16_bf16 v[32:47], v[132:135], v[148:151], v[32:47]
	ds_read_b64_tr_b16 v[148:149], v252 offset:25088
	ds_read_b64_tr_b16 v[150:151], v252 offset:27136
	v_add_f32_e32 v182, v98, v182
	v_add_f32_e32 v182, v99, v182
	v_cvt_pk_bf16_f32 v137, v98, v99
	v_exp_f32_e32 v102, v102
	v_mfma_f32_32x32x16_bf16 v[80:95], v[200:203], v[168:171], v[80:95]
	v_exp_f32_e32 v103, v103
	v_add_f32_e32 v182, v100, v182
	v_add_f32_e32 v182, v101, v182
	v_cvt_pk_bf16_f32 v138, v100, v101
	v_cvt_pk_bf16_f32 v139, v102, v103
	v_add_f32_e32 v182, v102, v182
	s_waitcnt lgkmcnt(6)
	v_mfma_f32_32x32x16_bf16 v[16:31], v[132:135], v[152:155], v[16:31]
	ds_read_b64_tr_b16 v[152:153], v252 offset:25600
	ds_read_b64_tr_b16 v[154:155], v252 offset:27648
	v_add_f32_e32 v182, v103, v182
	v_exp_f32_e32 v104, v104
	v_exp_f32_e32 v105, v105
	v_exp_f32_e32 v106, v106
	v_mfma_f32_32x32x16_bf16 v[64:79], v[204:207], v[168:171], v[64:79]
	v_exp_f32_e32 v107, v107
	v_add_f32_e32 v182, v104, v182
	v_add_f32_e32 v182, v105, v182
	v_cvt_pk_bf16_f32 v140, v104, v105
	s_waitcnt lgkmcnt(6)
	v_mfma_f32_32x32x16_bf16 v[0:15], v[132:135], v[156:159], v[0:15]
	ds_read_b64_tr_b16 v[156:157], v252 offset:26112
	ds_read_b64_tr_b16 v[158:159], v252 offset:28160
	v_exp_f32_e32 v108, v108
	v_exp_f32_e32 v109, v109
	v_add_f32_e32 v182, v106, v182
	v_add_f32_e32 v182, v107, v182
	v_mfma_f32_32x32x16_bf16 v[80:95], v[208:211], v[164:167], v[80:95]
	v_cvt_pk_bf16_f32 v141, v106, v107
	v_exp_f32_e32 v110, v110
	v_exp_f32_e32 v111, v111
	v_add_f32_e32 v182, v108, v182
	v_mfma_f32_32x32x16_bf16 v[64:79], v[212:215], v[164:167], v[64:79]
	v_add_f32_e32 v182, v109, v182
	v_cvt_pk_bf16_f32 v142, v108, v109
	v_cvt_pk_bf16_f32 v143, v110, v111
	v_add_f32_e32 v182, v110, v182
	v_add_f32_e32 v182, v111, v182
	s_cmp_lt_i32 s55, 0
	s_cselect_b32 s100, -1.0, 1.0
	v_mul_f32_e32 v185, s100, v186
	v_mfma_f32_32x32x16_bf16 v[80:95], v[216:219], v[160:163], v[80:95]
	v_fma_f32 v187, -v185, v183, s16
	v_fmamk_f32 v112, v185, 0x00000000, v187
	v_fmamk_f32 v113, v185, 0x3f800000, v187
	v_fmamk_f32 v114, v185, 0x40000000, v187
	v_fmamk_f32 v115, v185, 0x40400000, v187
	v_fmamk_f32 v116, v185, 0x41000000, v187
	v_mfma_f32_32x32x16_bf16 v[64:79], v[220:223], v[160:163], v[64:79]
	v_fmamk_f32 v117, v185, 0x41100000, v187
	v_fmamk_f32 v118, v185, 0x41200000, v187
	v_fmamk_f32 v119, v185, 0x41300000, v187
	v_fmamk_f32 v120, v185, 0x41800000, v187
	v_fmamk_f32 v121, v185, 0x41880000, v187
	v_fmamk_f32 v122, v185, 0x41900000, v187
	s_waitcnt lgkmcnt(6)
	v_mfma_f32_32x32x16_bf16 v[48:63], v[136:139], v[144:147], v[48:63]
	ds_read_b64_tr_b16 v[144:145], v252 offset:28672
	ds_read_b64_tr_b16 v[146:147], v252 offset:30720
	v_fmamk_f32 v123, v185, 0x41980000, v187
	v_fmamk_f32 v124, v185, 0x41c00000, v187
	v_fmamk_f32 v125, v185, 0x41c80000, v187
	v_fmamk_f32 v126, v185, 0x41d00000, v187
	v_fmamk_f32 v127, v185, 0x41d80000, v187
	v_fmamk_f32 v96, v185, 0x42000000, v187
	s_waitcnt lgkmcnt(6)
; template <int KS> __device__ __forceinline__ void pv_ks(f32x16* o, int vb, bf16x8 pa) {
;     const s16x4 l0 = tr_read<v_rd_off(0, KS, 0)>(vb), h0 = tr_read<v_rd_off(0, KS, 1)>(vb), l1 = tr_read<v_rd_off(1, KS, 0)>(vb), h1 = tr_read<v_rd_off(1, KS, 1)>(vb);
;     const s16x4 l2 = tr_read<v_rd_off(2, KS, 0)>(vb), h2 = tr_read<v_rd_off(2, KS, 1)>(vb), l3 = tr_read<v_rd_off(3, KS, 0)>(vb), h3 = tr_read<v_rd_off(3, KS, 1)>(vb);
;     ...
;     asm volatile("s_waitcnt lgkmcnt(6)" ::: "memory"); SBAR();
;     o[0] = __builtin_amdgcn_mfma_f32_32x32x16_bf16(pa, PK(l0, h0), o[0], 0, 0, 0);
;     asm volatile("s_waitcnt lgkmcnt(4)" ::: "memory"); SBAR();
;     o[1] = __builtin_amdgcn_mfma_f32_32x32x16_bf16(pa, PK(l1, h1), o[1], 0, 0, 0);
;     asm volatile("s_waitcnt lgkmcnt(2)" ::: "memory"); SBAR();
;     o[2] = __builtin_amdgcn_mfma_f32_32x32x16_bf16(pa, PK(l2, h2), o[2], 0, 0, 0);
;     asm volatile("s_waitcnt lgkmcnt(0)" ::: "memory"); SBAR();
;     o[3] = __builtin_amdgcn_mfma_f32_32x32x16_bf16(pa, PK(l3, h3), o[3], 0, 0, 0);
;     ...
; }
; __device__ __forceinline__ void pv_d0(f32x16* o, int vb, bf16x8 pa0, bf16x8 pa1, bf16x8 pa2, bf16x8 pa3) {
;     __builtin_amdgcn_s_setprio(1);
;     pv_ks<0>(o, vb, pa0); pv_ks<1>(o, vb, pa1); pv_ks<2>(o, vb, pa2); pv_ks<3>(o, vb, pa3);
;     __builtin_amdgcn_s_setprio(0);
; }
; __device__ __forceinline__ void exp_half(f32x16& p) {
; #pragma unroll
;     for (int r = 0; r < 16; ++r) p[r] = __builtin_amdgcn_exp2f(p[r]);
; }
; __device__ __forceinline__ void pack_p(const f32x16& p0, const f32x16& p1, float& l_reg, bf16x8& pa0, bf16x8& pa1, bf16x8& pa2, bf16x8& pa3) {
;     float ps = 0;
; #pragma unroll
;     for (int r = 0; r < 16; ++r) ps += p0[r];
; #pragma unroll
;     for (int r = 0; r < 16; ++r) ps += p1[r];
;     l_reg += ps;
;     ...
;     PK4(p0, 0, pa0); PK4(p0, 8, pa1); PK4(p1, 0, pa2); PK4(p1, 8, pa3);
;     ...
; }
; template <int ND0> __device__ __forceinline__ void qkt(f32x16& p0, f32x16& p1, const char* Ks, const bf16x8* qr, int r32, int hi, int colB0) {
; #pragma unroll
;     for (int d0 = 0; d0 < ND0; ++d0) { const int cb = colB0 + (d0 * 16 + hi * 8) * 2;
;         const bf16x8 b0 = *reinterpret_cast<const bf16x8*>(Ks + KSWZ(r32, cb));
;         const bf16x8 b1 = *reinterpret_cast<const bf16x8*>(Ks + KSWZ(32 + r32, cb));
;         p0 = __builtin_amdgcn_mfma_f32_32x32x16_bf16(b0, qr[d0], p0, 0, 0, 0);
	v_mfma_f32_32x32x16_bf16 v[32:47], v[136:139], v[148:151], v[32:47]
	ds_read_b64_tr_b16 v[148:149], v252 offset:29184
	ds_read_b64_tr_b16 v[150:151], v252 offset:31232
	v_fmamk_f32 v97, v185, 0x42040000, v187
	v_fmamk_f32 v98, v185, 0x42080000, v187
	v_fmamk_f32 v99, v185, 0x420c0000, v187
	v_fmamk_f32 v100, v185, 0x42200000, v187
	v_fmamk_f32 v101, v185, 0x42240000, v187
	v_fmamk_f32 v102, v185, 0x42280000, v187
	s_waitcnt lgkmcnt(6)
	v_mfma_f32_32x32x16_bf16 v[16:31], v[136:139], v[152:155], v[16:31]
	ds_read_b64_tr_b16 v[152:153], v252 offset:29696
	ds_read_b64_tr_b16 v[154:155], v252 offset:31744
	v_fmamk_f32 v103, v185, 0x422c0000, v187
	v_fmamk_f32 v104, v185, 0x42400000, v187
	v_fmamk_f32 v105, v185, 0x42440000, v187
	v_fmamk_f32 v106, v185, 0x42480000, v187
	v_fmamk_f32 v107, v185, 0x424c0000, v187
	v_fmamk_f32 v108, v185, 0x42600000, v187
	s_waitcnt lgkmcnt(6)
	v_mfma_f32_32x32x16_bf16 v[0:15], v[136:139], v[156:159], v[0:15]
	ds_read_b64_tr_b16 v[156:157], v252 offset:30208
	ds_read_b64_tr_b16 v[158:159], v252 offset:32256
	v_fmamk_f32 v109, v185, 0x42640000, v187
	v_fmamk_f32 v110, v185, 0x42680000, v187
	v_fmamk_f32 v111, v185, 0x426c0000, v187
	v_exp_f32_e32 v80, v80
	v_exp_f32_e32 v81, v81
	s_waitcnt lgkmcnt(6)
	v_mfma_f32_32x32x16_bf16 v[48:63], v[140:143], v[144:147], v[48:63]
	ds_read_b64_tr_b16 v[144:145], v252 offset:32768
	ds_read_b64_tr_b16 v[146:147], v252 offset:34816
	v_exp_f32_e32 v82, v82
	v_exp_f32_e32 v83, v83
	v_add_f32_e32 v182, v80, v182
	v_add_f32_e32 v182, v81, v182
	s_waitcnt lgkmcnt(6)
	v_mfma_f32_32x32x16_bf16 v[32:47], v[140:143], v[148:151], v[32:47]
	ds_read_b64_tr_b16 v[148:149], v252 offset:33280
	ds_read_b64_tr_b16 v[150:151], v252 offset:35328
	v_cvt_pk_bf16_f32 v128, v80, v81
	v_exp_f32_e32 v84, v84
	v_exp_f32_e32 v85, v85
	v_add_f32_e32 v182, v82, v182
	s_waitcnt lgkmcnt(6)
	v_mfma_f32_32x32x16_bf16 v[16:31], v[140:143], v[152:155], v[16:31]
	ds_read_b64_tr_b16 v[152:153], v252 offset:33792
	ds_read_b64_tr_b16 v[154:155], v252 offset:35840
	v_add_f32_e32 v182, v83, v182
	v_cvt_pk_bf16_f32 v129, v82, v83
	v_exp_f32_e32 v86, v86
	v_exp_f32_e32 v87, v87
	s_waitcnt lgkmcnt(6)
	v_mfma_f32_32x32x16_bf16 v[0:15], v[140:143], v[156:159], v[0:15]
	ds_read_b64_tr_b16 v[156:157], v252 offset:34304
	ds_read_b64_tr_b16 v[158:159], v252 offset:36352
	v_add_f32_e32 v182, v84, v182
	v_add_f32_e32 v182, v85, v182
	v_cvt_pk_bf16_f32 v130, v84, v85
	v_cvt_pk_bf16_f32 v131, v86, v87
	v_add_f32_e32 v182, v86, v182
	v_add_f32_e32 v182, v87, v182
	s_add_i32 s100, s55, 62
	s_cmp_lt_u32 s100, 93
	s_cbranch_scc0 .Lsym_nodiag_s1
	v_add_f32_e32 v190, 0x00000000, v183
	v_add_f32_e32 v191, 0xc2000000, v183
	v_fma_f32 v112, |v190|, v186, s16
	v_fma_f32 v96, |v191|, v186, s16
	v_add_f32_e32 v190, 0xbf800000, v183
	v_add_f32_e32 v191, 0xc2040000, v183
	v_fma_f32 v113, |v190|, v186, s16
	v_fma_f32 v97, |v191|, v186, s16
	v_add_f32_e32 v190, 0xc0000000, v183
	v_add_f32_e32 v191, 0xc2080000, v183
	v_fma_f32 v114, |v190|, v186, s16
	v_fma_f32 v98, |v191|, v186, s16
	v_add_f32_e32 v190, 0xc0400000, v183
	v_add_f32_e32 v191, 0xc20c0000, v183
	v_fma_f32 v115, |v190|, v186, s16
	v_fma_f32 v99, |v191|, v186, s16
	v_add_f32_e32 v190, 0xc1000000, v183
	v_add_f32_e32 v191, 0xc2200000, v183
	v_fma_f32 v116, |v190|, v186, s16
	v_fma_f32 v100, |v191|, v186, s16
	v_add_f32_e32 v190, 0xc1100000, v183
	v_add_f32_e32 v191, 0xc2240000, v183
	v_fma_f32 v117, |v190|, v186, s16
	v_fma_f32 v101, |v191|, v186, s16
	v_add_f32_e32 v190, 0xc1200000, v183
	v_add_f32_e32 v191, 0xc2280000, v183
	v_fma_f32 v118, |v190|, v186, s16
	v_fma_f32 v102, |v191|, v186, s16
	v_add_f32_e32 v190, 0xc1300000, v183
	v_add_f32_e32 v191, 0xc22c0000, v183
	v_fma_f32 v119, |v190|, v186, s16
	v_fma_f32 v103, |v191|, v186, s16
	v_add_f32_e32 v190, 0xc1800000, v183
	v_add_f32_e32 v191, 0xc2400000, v183
	v_fma_f32 v120, |v190|, v186, s16
	v_fma_f32 v104, |v191|, v186, s16
	v_add_f32_e32 v190, 0xc1880000, v183
	v_add_f32_e32 v191, 0xc2440000, v183
	v_fma_f32 v121, |v190|, v186, s16
	v_fma_f32 v105, |v191|, v186, s16
	v_add_f32_e32 v190, 0xc1900000, v183
	v_add_f32_e32 v191, 0xc2480000, v183
	v_fma_f32 v122, |v190|, v186, s16
	v_fma_f32 v106, |v191|, v186, s16
	v_add_f32_e32 v190, 0xc1980000, v183
	v_add_f32_e32 v191, 0xc24c0000, v183
	v_fma_f32 v123, |v190|, v186, s16
	v_fma_f32 v107, |v191|, v186, s16
	v_add_f32_e32 v190, 0xc1c00000, v183
	v_add_f32_e32 v191, 0xc2600000, v183
	v_fma_f32 v124, |v190|, v186, s16
	v_fma_f32 v108, |v191|, v186, s16
	v_add_f32_e32 v190, 0xc1c80000, v183
	v_add_f32_e32 v191, 0xc2640000, v183
	v_fma_f32 v125, |v190|, v186, s16
	v_fma_f32 v109, |v191|, v186, s16
	v_add_f32_e32 v190, 0xc1d00000, v183
	v_add_f32_e32 v191, 0xc2680000, v183
	v_fma_f32 v126, |v190|, v186, s16
	v_fma_f32 v110, |v191|, v186, s16
	v_add_f32_e32 v190, 0xc1d80000, v183
	v_add_f32_e32 v191, 0xc26c0000, v183
	v_fma_f32 v127, |v190|, v186, s16
	v_fma_f32 v111, |v191|, v186, s16

; template <int KS> __device__ __forceinline__ void pv_ks(f32x16* o, int vb, bf16x8 pa) {
;     const s16x4 l0 = tr_read<v_rd_off(0, KS, 0)>(vb), h0 = tr_read<v_rd_off(0, KS, 1)>(vb), l1 = tr_read<v_rd_off(1, KS, 0)>(vb), h1 = tr_read<v_rd_off(1, KS, 1)>(vb);
;     const s16x4 l2 = tr_read<v_rd_off(2, KS, 0)>(vb), h2 = tr_read<v_rd_off(2, KS, 1)>(vb), l3 = tr_read<v_rd_off(3, KS, 0)>(vb), h3 = tr_read<v_rd_off(3, KS, 1)>(vb);
;     ...
;     asm volatile("s_waitcnt lgkmcnt(6)" ::: "memory"); SBAR();
;     o[0] = __builtin_amdgcn_mfma_f32_32x32x16_bf16(pa, PK(l0, h0), o[0], 0, 0, 0);
;     asm volatile("s_waitcnt lgkmcnt(4)" ::: "memory"); SBAR();
;     o[1] = __builtin_amdgcn_mfma_f32_32x32x16_bf16(pa, PK(l1, h1), o[1], 0, 0, 0);
;     asm volatile("s_waitcnt lgkmcnt(2)" ::: "memory"); SBAR();
;     o[2] = __builtin_amdgcn_mfma_f32_32x32x16_bf16(pa, PK(l2, h2), o[2], 0, 0, 0);
;     asm volatile("s_waitcnt lgkmcnt(0)" ::: "memory"); SBAR();
;     o[3] = __builtin_amdgcn_mfma_f32_32x32x16_bf16(pa, PK(l3, h3), o[3], 0, 0, 0);
;     ...
; }
; __device__ __forceinline__ void pv_d0(f32x16* o, int vb, bf16x8 pa0, bf16x8 pa1, bf16x8 pa2, bf16x8 pa3) {
;     __builtin_amdgcn_s_setprio(1);
;     pv_ks<0>(o, vb, pa0); pv_ks<1>(o, vb, pa1); pv_ks<2>(o, vb, pa2); pv_ks<3>(o, vb, pa3);
;     __builtin_amdgcn_s_setprio(0);
; }
; __device__ __forceinline__ void exp_half(f32x16& p) {
; #pragma unroll
;     for (int r = 0; r < 16; ++r) p[r] = __builtin_amdgcn_exp2f(p[r]);
; }
; __device__ __forceinline__ void pack_p(const f32x16& p0, const f32x16& p1, float& l_reg, bf16x8& pa0, bf16x8& pa1, bf16x8& pa2, bf16x8& pa3) {
;     float ps = 0;
; #pragma unroll
;     for (int r = 0; r < 16; ++r) ps += p0[r];
; #pragma unroll
;     for (int r = 0; r < 16; ++r) ps += p1[r];
;     l_reg += ps;
;     ...
;     PK4(p0, 0, pa0); PK4(p0, 8, pa1); PK4(p1, 0, pa2); PK4(p1, 8, pa3);
;     ...
; }
; template <int ND0> __device__ __forceinline__ void qkt(f32x16& p0, f32x16& p1, const char* Ks, const bf16x8* qr, int r32, int hi, int colB0) {
; #pragma unroll
;     for (int d0 = 0; d0 < ND0; ++d0) { const int cb = colB0 + (d0 * 16 + hi * 8) * 2;
;         const bf16x8 b0 = *reinterpret_cast<const bf16x8*>(Ks + KSWZ(r32, cb));
;         const bf16x8 b1 = *reinterpret_cast<const bf16x8*>(Ks + KSWZ(32 + r32, cb));
;         p0 = __builtin_amdgcn_mfma_f32_32x32x16_bf16(b0, qr[d0], p0, 0, 0, 0);
.Lsym_nostage_s2:
	s_waitcnt lgkmcnt(14)
	v_mfma_f32_32x32x16_bf16 v[48:63], v[128:131], v[144:147], v[48:63]
	ds_read_b64_tr_b16 v[144:145], v252 offset:36864
	ds_read_b64_tr_b16 v[146:147], v252 offset:38912
	v_exp_f32_e32 v88, v88
	v_exp_f32_e32 v89, v89
	v_exp_f32_e32 v90, v90
	s_waitcnt lgkmcnt(14)
	v_mfma_f32_32x32x16_bf16 v[32:47], v[128:131], v[148:151], v[32:47]
	ds_read_b64_tr_b16 v[148:149], v252 offset:37376
	ds_read_b64_tr_b16 v[150:151], v252 offset:39424
	v_exp_f32_e32 v91, v91
	v_add_f32_e32 v182, v88, v182
	v_add_f32_e32 v182, v89, v182
	v_cvt_pk_bf16_f32 v132, v88, v89
	v_exp_f32_e32 v92, v92
	s_waitcnt lgkmcnt(14)
	v_mfma_f32_32x32x16_bf16 v[16:31], v[128:131], v[152:155], v[16:31]
	ds_read_b64_tr_b16 v[152:153], v252 offset:37888
	ds_read_b64_tr_b16 v[154:155], v252 offset:39936
	v_exp_f32_e32 v93, v93
	v_add_f32_e32 v182, v90, v182
	v_add_f32_e32 v182, v91, v182
	v_cvt_pk_bf16_f32 v133, v90, v91
	s_waitcnt lgkmcnt(14)
	v_mfma_f32_32x32x16_bf16 v[0:15], v[128:131], v[156:159], v[0:15]
	ds_read_b64_tr_b16 v[156:157], v252 offset:38400
	ds_read_b64_tr_b16 v[158:159], v252 offset:40448
	v_exp_f32_e32 v94, v94
	v_exp_f32_e32 v95, v95
	v_add_f32_e32 v182, v92, v182
	v_add_f32_e32 v182, v93, v182
	s_waitcnt lgkmcnt(15)
	v_mfma_f32_32x32x16_bf16 v[112:127], v[192:195], v[172:175], v[112:127]
	v_cvt_pk_bf16_f32 v134, v92, v93
	v_cvt_pk_bf16_f32 v135, v94, v95
	v_add_f32_e32 v182, v94, v182
	v_add_f32_e32 v182, v95, v182
	v_exp_f32_e32 v64, v64
	s_waitcnt lgkmcnt(6)
	v_mfma_f32_32x32x16_bf16 v[48:63], v[132:135], v[144:147], v[48:63]
	ds_read_b64_tr_b16 v[144:145], v252 offset:40960
	ds_read_b64_tr_b16 v[146:147], v252 offset:43008
	v_exp_f32_e32 v65, v65
	v_exp_f32_e32 v66, v66
	v_exp_f32_e32 v67, v67
	v_add_f32_e32 v182, v64, v182
	v_mfma_f32_32x32x16_bf16 v[96:111], v[196:199], v[172:175], v[96:111]
	v_add_f32_e32 v182, v65, v182
	v_cvt_pk_bf16_f32 v136, v64, v65
	v_exp_f32_e32 v68, v68
	v_exp_f32_e32 v69, v69
	s_waitcnt lgkmcnt(6)
	v_mfma_f32_32x32x16_bf16 v[32:47], v[132:135], v[148:151], v[32:47]
	ds_read_b64_tr_b16 v[148:149], v252 offset:41472
	ds_read_b64_tr_b16 v[150:151], v252 offset:43520
	v_add_f32_e32 v182, v66, v182
	v_add_f32_e32 v182, v67, v182
	v_cvt_pk_bf16_f32 v137, v66, v67
	v_exp_f32_e32 v70, v70
	v_mfma_f32_32x32x16_bf16 v[112:127], v[200:203], v[168:171], v[112:127]
	v_exp_f32_e32 v71, v71
	v_add_f32_e32 v182, v68, v182
	v_add_f32_e32 v182, v69, v182
	v_cvt_pk_bf16_f32 v138, v68, v69
	v_cvt_pk_bf16_f32 v139, v70, v71
	v_add_f32_e32 v182, v70, v182
	s_waitcnt lgkmcnt(6)
	v_mfma_f32_32x32x16_bf16 v[16:31], v[132:135], v[152:155], v[16:31]
	ds_read_b64_tr_b16 v[152:153], v252 offset:41984
	ds_read_b64_tr_b16 v[154:155], v252 offset:44032
	v_add_f32_e32 v182, v71, v182
	v_exp_f32_e32 v72, v72
	v_exp_f32_e32 v73, v73
	v_exp_f32_e32 v74, v74
	v_mfma_f32_32x32x16_bf16 v[96:111], v[204:207], v[168:171], v[96:111]
	v_exp_f32_e32 v75, v75
	v_add_f32_e32 v182, v72, v182
	v_add_f32_e32 v182, v73, v182
	v_cvt_pk_bf16_f32 v140, v72, v73
	s_waitcnt lgkmcnt(6)
	v_mfma_f32_32x32x16_bf16 v[0:15], v[132:135], v[156:159], v[0:15]
	ds_read_b64_tr_b16 v[156:157], v252 offset:42496
	ds_read_b64_tr_b16 v[158:159], v252 offset:44544
	v_exp_f32_e32 v76, v76
	v_exp_f32_e32 v77, v77
	v_add_f32_e32 v182, v74, v182
	v_add_f32_e32 v182, v75, v182
	v_mfma_f32_32x32x16_bf16 v[112:127], v[208:211], v[164:167], v[112:127]
	v_cvt_pk_bf16_f32 v141, v74, v75
	v_exp_f32_e32 v78, v78
	v_exp_f32_e32 v79, v79
	v_add_f32_e32 v182, v76, v182
	v_mfma_f32_32x32x16_bf16 v[96:111], v[212:215], v[164:167], v[96:111]
	v_add_f32_e32 v182, v77, v182
	v_cvt_pk_bf16_f32 v142, v76, v77
	v_cvt_pk_bf16_f32 v143, v78, v79
	v_add_f32_e32 v182, v78, v182
	v_add_f32_e32 v182, v79, v182
	s_cmp_lt_i32 s55, 0
	s_cselect_b32 s100, -1.0, 1.0
	v_mul_f32_e32 v185, s100, v186
	v_mfma_f32_32x32x16_bf16 v[112:127], v[216:219], v[160:163], v[112:127]
	v_fma_f32 v187, -v185, v183, s16
	v_fmamk_f32 v80, v185, 0x00000000, v187
	v_fmamk_f32 v81, v185, 0x3f800000, v187
	v_fmamk_f32 v82, v185, 0x40000000, v187
	v_fmamk_f32 v83, v185, 0x40400000, v187
	v_fmamk_f32 v84, v185, 0x41000000, v187
	v_mfma_f32_32x32x16_bf16 v[96:111], v[220:223], v[160:163], v[96:111]
	v_fmamk_f32 v85, v185, 0x41100000, v187
	v_fmamk_f32 v86, v185, 0x41200000, v187
	v_fmamk_f32 v87, v185, 0x41300000, v187
	v_fmamk_f32 v88, v185, 0x41800000, v187
	v_fmamk_f32 v89, v185, 0x41880000, v187
	v_fmamk_f32 v90, v185, 0x41900000, v187
	s_waitcnt lgkmcnt(6)
	v_mfma_f32_32x32x16_bf16 v[48:63], v[136:139], v[144:147], v[48:63]
	ds_read_b64_tr_b16 v[144:145], v252 offset:45056
	ds_read_b64_tr_b16 v[146:147], v252 offset:47104
	v_fmamk_f32 v91, v185, 0x41980000, v187
	v_fmamk_f32 v92, v185, 0x41c00000, v187
	v_fmamk_f32 v93, v185, 0x41c80000, v187
	v_fmamk_f32 v94, v185, 0x41d00000, v187
	v_fmamk_f32 v95, v185, 0x41d80000, v187
	v_fmamk_f32 v64, v185, 0x42000000, v187
	s_waitcnt lgkmcnt(6)
; template <int KS> __device__ __forceinline__ void pv_ks(f32x16* o, int vb, bf16x8 pa) {
;     const s16x4 l0 = tr_read<v_rd_off(0, KS, 0)>(vb), h0 = tr_read<v_rd_off(0, KS, 1)>(vb), l1 = tr_read<v_rd_off(1, KS, 0)>(vb), h1 = tr_read<v_rd_off(1, KS, 1)>(vb);
;     const s16x4 l2 = tr_read<v_rd_off(2, KS, 0)>(vb), h2 = tr_read<v_rd_off(2, KS, 1)>(vb), l3 = tr_read<v_rd_off(3, KS, 0)>(vb), h3 = tr_read<v_rd_off(3, KS, 1)>(vb);
;     ...
;     asm volatile("s_waitcnt lgkmcnt(6)" ::: "memory"); SBAR();
;     o[0] = __builtin_amdgcn_mfma_f32_32x32x16_bf16(pa, PK(l0, h0), o[0], 0, 0, 0);
;     asm volatile("s_waitcnt lgkmcnt(4)" ::: "memory"); SBAR();
;     o[1] = __builtin_amdgcn_mfma_f32_32x32x16_bf16(pa, PK(l1, h1), o[1], 0, 0, 0);
;     asm volatile("s_waitcnt lgkmcnt(2)" ::: "memory"); SBAR();
;     o[2] = __builtin_amdgcn_mfma_f32_32x32x16_bf16(pa, PK(l2, h2), o[2], 0, 0, 0);
;     asm volatile("s_waitcnt lgkmcnt(0)" ::: "memory"); SBAR();
;     o[3] = __builtin_amdgcn_mfma_f32_32x32x16_bf16(pa, PK(l3, h3), o[3], 0, 0, 0);
;     ...
; }
; __device__ __forceinline__ void pv_d0(f32x16* o, int vb, bf16x8 pa0, bf16x8 pa1, bf16x8 pa2, bf16x8 pa3) {
;     __builtin_amdgcn_s_setprio(1);
;     pv_ks<0>(o, vb, pa0); pv_ks<1>(o, vb, pa1); pv_ks<2>(o, vb, pa2); pv_ks<3>(o, vb, pa3);
;     __builtin_amdgcn_s_setprio(0);
; }
; __device__ __forceinline__ void exp_half(f32x16& p) {
; #pragma unroll
;     for (int r = 0; r < 16; ++r) p[r] = __builtin_amdgcn_exp2f(p[r]);
; }
; __device__ __forceinline__ void pack_p(const f32x16& p0, const f32x16& p1, float& l_reg, bf16x8& pa0, bf16x8& pa1, bf16x8& pa2, bf16x8& pa3) {
;     float ps = 0;
; #pragma unroll
;     for (int r = 0; r < 16; ++r) ps += p0[r];
; #pragma unroll
;     for (int r = 0; r < 16; ++r) ps += p1[r];
;     l_reg += ps;
;     ...
;     PK4(p0, 0, pa0); PK4(p0, 8, pa1); PK4(p1, 0, pa2); PK4(p1, 8, pa3);
;     ...
; }
; template <int ND0> __device__ __forceinline__ void qkt(f32x16& p0, f32x16& p1, const char* Ks, const bf16x8* qr, int r32, int hi, int colB0) {
; #pragma unroll
;     for (int d0 = 0; d0 < ND0; ++d0) { const int cb = colB0 + (d0 * 16 + hi * 8) * 2;
;         const bf16x8 b0 = *reinterpret_cast<const bf16x8*>(Ks + KSWZ(r32, cb));
;         const bf16x8 b1 = *reinterpret_cast<const bf16x8*>(Ks + KSWZ(32 + r32, cb));
;         p0 = __builtin_amdgcn_mfma_f32_32x32x16_bf16(b0, qr[d0], p0, 0, 0, 0);
	v_mfma_f32_32x32x16_bf16 v[32:47], v[136:139], v[148:151], v[32:47]
	ds_read_b64_tr_b16 v[148:149], v252 offset:45568
	ds_read_b64_tr_b16 v[150:151], v252 offset:47616
	v_fmamk_f32 v65, v185, 0x42040000, v187
	v_fmamk_f32 v66, v185, 0x42080000, v187
	v_fmamk_f32 v67, v185, 0x420c0000, v187
	v_fmamk_f32 v68, v185, 0x42200000, v187
	v_fmamk_f32 v69, v185, 0x42240000, v187
	v_fmamk_f32 v70, v185, 0x42280000, v187
	s_waitcnt lgkmcnt(6)
	v_mfma_f32_32x32x16_bf16 v[16:31], v[136:139], v[152:155], v[16:31]
	ds_read_b64_tr_b16 v[152:153], v252 offset:46080
	ds_read_b64_tr_b16 v[154:155], v252 offset:48128
	v_fmamk_f32 v71, v185, 0x422c0000, v187
	v_fmamk_f32 v72, v185, 0x42400000, v187
	v_fmamk_f32 v73, v185, 0x42440000, v187
	v_fmamk_f32 v74, v185, 0x42480000, v187
	v_fmamk_f32 v75, v185, 0x424c0000, v187
	v_fmamk_f32 v76, v185, 0x42600000, v187
	s_waitcnt lgkmcnt(6)
	v_mfma_f32_32x32x16_bf16 v[0:15], v[136:139], v[156:159], v[0:15]
	ds_read_b64_tr_b16 v[156:157], v252 offset:46592
	ds_read_b64_tr_b16 v[158:159], v252 offset:48640
	v_fmamk_f32 v77, v185, 0x42640000, v187
	v_fmamk_f32 v78, v185, 0x42680000, v187
	v_fmamk_f32 v79, v185, 0x426c0000, v187
	v_exp_f32_e32 v112, v112
	v_exp_f32_e32 v113, v113
	s_waitcnt lgkmcnt(6)
	v_mfma_f32_32x32x16_bf16 v[48:63], v[140:143], v[144:147], v[48:63]
	ds_read_b64_tr_b16 v[144:145], v252 offset:49152
	ds_read_b64_tr_b16 v[146:147], v252 offset:51200
	v_exp_f32_e32 v114, v114
	v_exp_f32_e32 v115, v115
	v_add_f32_e32 v182, v112, v182
	v_add_f32_e32 v182, v113, v182
	s_waitcnt lgkmcnt(6)
	v_mfma_f32_32x32x16_bf16 v[32:47], v[140:143], v[148:151], v[32:47]
	ds_read_b64_tr_b16 v[148:149], v252 offset:49664
	ds_read_b64_tr_b16 v[150:151], v252 offset:51712
	v_cvt_pk_bf16_f32 v128, v112, v113
	v_exp_f32_e32 v116, v116
	v_exp_f32_e32 v117, v117
	v_add_f32_e32 v182, v114, v182
	s_waitcnt lgkmcnt(6)
	v_mfma_f32_32x32x16_bf16 v[16:31], v[140:143], v[152:155], v[16:31]
	ds_read_b64_tr_b16 v[152:153], v252 offset:50176
	ds_read_b64_tr_b16 v[154:155], v252 offset:52224
	v_add_f32_e32 v182, v115, v182
	v_cvt_pk_bf16_f32 v129, v114, v115
	v_exp_f32_e32 v118, v118
	v_exp_f32_e32 v119, v119
	s_waitcnt lgkmcnt(6)
	v_mfma_f32_32x32x16_bf16 v[0:15], v[140:143], v[156:159], v[0:15]
	ds_read_b64_tr_b16 v[156:157], v252 offset:50688
	ds_read_b64_tr_b16 v[158:159], v252 offset:52736
	v_add_f32_e32 v182, v116, v182
	v_add_f32_e32 v182, v117, v182
	v_cvt_pk_bf16_f32 v130, v116, v117
	v_cvt_pk_bf16_f32 v131, v118, v119
	v_add_f32_e32 v182, v118, v182
	v_add_f32_e32 v182, v119, v182
	s_add_i32 s100, s55, 62
	s_cmp_lt_u32 s100, 93
	s_cbranch_scc0 .Lsym_nodiag_s2
	v_add_f32_e32 v190, 0x00000000, v183
	v_add_f32_e32 v191, 0xc2000000, v183
	v_fma_f32 v80, |v190|, v186, s16
	v_fma_f32 v64, |v191|, v186, s16
	v_add_f32_e32 v190, 0xbf800000, v183
	v_add_f32_e32 v191, 0xc2040000, v183
	v_fma_f32 v81, |v190|, v186, s16
	v_fma_f32 v65, |v191|, v186, s16
	v_add_f32_e32 v190, 0xc0000000, v183
	v_add_f32_e32 v191, 0xc2080000, v183
	v_fma_f32 v82, |v190|, v186, s16
	v_fma_f32 v66, |v191|, v186, s16
	v_add_f32_e32 v190, 0xc0400000, v183
	v_add_f32_e32 v191, 0xc20c0000, v183
	v_fma_f32 v83, |v190|, v186, s16
	v_fma_f32 v67, |v191|, v186, s16
	v_add_f32_e32 v190, 0xc1000000, v183
	v_add_f32_e32 v191, 0xc2200000, v183
	v_fma_f32 v84, |v190|, v186, s16
	v_fma_f32 v68, |v191|, v186, s16
	v_add_f32_e32 v190, 0xc1100000, v183
	v_add_f32_e32 v191, 0xc2240000, v183
	v_fma_f32 v85, |v190|, v186, s16
	v_fma_f32 v69, |v191|, v186, s16
	v_add_f32_e32 v190, 0xc1200000, v183
	v_add_f32_e32 v191, 0xc2280000, v183
	v_fma_f32 v86, |v190|, v186, s16
	v_fma_f32 v70, |v191|, v186, s16
	v_add_f32_e32 v190, 0xc1300000, v183
	v_add_f32_e32 v191, 0xc22c0000, v183
	v_fma_f32 v87, |v190|, v186, s16
	v_fma_f32 v71, |v191|, v186, s16
	v_add_f32_e32 v190, 0xc1800000, v183
	v_add_f32_e32 v191, 0xc2400000, v183
	v_fma_f32 v88, |v190|, v186, s16
	v_fma_f32 v72, |v191|, v186, s16
	v_add_f32_e32 v190, 0xc1880000, v183
	v_add_f32_e32 v191, 0xc2440000, v183
	v_fma_f32 v89, |v190|, v186, s16
	v_fma_f32 v73, |v191|, v186, s16
	v_add_f32_e32 v190, 0xc1900000, v183
	v_add_f32_e32 v191, 0xc2480000, v183
	v_fma_f32 v90, |v190|, v186, s16
	v_fma_f32 v74, |v191|, v186, s16
	v_add_f32_e32 v190, 0xc1980000, v183
	v_add_f32_e32 v191, 0xc24c0000, v183
	v_fma_f32 v91, |v190|, v186, s16
	v_fma_f32 v75, |v191|, v186, s16
	v_add_f32_e32 v190, 0xc1c00000, v183
	v_add_f32_e32 v191, 0xc2600000, v183
	v_fma_f32 v92, |v190|, v186, s16
	v_fma_f32 v76, |v191|, v186, s16
	v_add_f32_e32 v190, 0xc1c80000, v183
	v_add_f32_e32 v191, 0xc2640000, v183
	v_fma_f32 v93, |v190|, v186, s16
	v_fma_f32 v77, |v191|, v186, s16
	v_add_f32_e32 v190, 0xc1d00000, v183
	v_add_f32_e32 v191, 0xc2680000, v183
	v_fma_f32 v94, |v190|, v186, s16
	v_fma_f32 v78, |v191|, v186, s16
	v_add_f32_e32 v190, 0xc1d80000, v183
	v_add_f32_e32 v191, 0xc26c0000, v183
	v_fma_f32 v95, |v190|, v186, s16
	v_fma_f32 v79, |v191|, v186, s16

; template <int KS> __device__ __forceinline__ void pv_ks(f32x16* o, int vb, bf16x8 pa) {
;     const s16x4 l0 = tr_read<v_rd_off(0, KS, 0)>(vb), h0 = tr_read<v_rd_off(0, KS, 1)>(vb), l1 = tr_read<v_rd_off(1, KS, 0)>(vb), h1 = tr_read<v_rd_off(1, KS, 1)>(vb);
;     const s16x4 l2 = tr_read<v_rd_off(2, KS, 0)>(vb), h2 = tr_read<v_rd_off(2, KS, 1)>(vb), l3 = tr_read<v_rd_off(3, KS, 0)>(vb), h3 = tr_read<v_rd_off(3, KS, 1)>(vb);
;     ...
;     asm volatile("s_waitcnt lgkmcnt(6)" ::: "memory"); SBAR();
;     o[0] = __builtin_amdgcn_mfma_f32_32x32x16_bf16(pa, PK(l0, h0), o[0], 0, 0, 0);
;     asm volatile("s_waitcnt lgkmcnt(4)" ::: "memory"); SBAR();
;     o[1] = __builtin_amdgcn_mfma_f32_32x32x16_bf16(pa, PK(l1, h1), o[1], 0, 0, 0);
;     asm volatile("s_waitcnt lgkmcnt(2)" ::: "memory"); SBAR();
;     o[2] = __builtin_amdgcn_mfma_f32_32x32x16_bf16(pa, PK(l2, h2), o[2], 0, 0, 0);
;     asm volatile("s_waitcnt lgkmcnt(0)" ::: "memory"); SBAR();
;     o[3] = __builtin_amdgcn_mfma_f32_32x32x16_bf16(pa, PK(l3, h3), o[3], 0, 0, 0);
;     ...
; }
; __device__ __forceinline__ void pv_d0(f32x16* o, int vb, bf16x8 pa0, bf16x8 pa1, bf16x8 pa2, bf16x8 pa3) {
;     __builtin_amdgcn_s_setprio(1);
;     pv_ks<0>(o, vb, pa0); pv_ks<1>(o, vb, pa1); pv_ks<2>(o, vb, pa2); pv_ks<3>(o, vb, pa3);
;     __builtin_amdgcn_s_setprio(0);
; }
; __device__ __forceinline__ void exp_half(f32x16& p) {
; #pragma unroll
;     for (int r = 0; r < 16; ++r) p[r] = __builtin_amdgcn_exp2f(p[r]);
; }
; __device__ __forceinline__ void pack_p(const f32x16& p0, const f32x16& p1, float& l_reg, bf16x8& pa0, bf16x8& pa1, bf16x8& pa2, bf16x8& pa3) {
;     float ps = 0;
; #pragma unroll
;     for (int r = 0; r < 16; ++r) ps += p0[r];
; #pragma unroll
;     for (int r = 0; r < 16; ++r) ps += p1[r];
;     l_reg += ps;
;     ...
;     PK4(p0, 0, pa0); PK4(p0, 8, pa1); PK4(p1, 0, pa2); PK4(p1, 8, pa3);
;     ...
; }
; template <int ND0> __device__ __forceinline__ void qkt(f32x16& p0, f32x16& p1, const char* Ks, const bf16x8* qr, int r32, int hi, int colB0) {
; #pragma unroll
;     for (int d0 = 0; d0 < ND0; ++d0) { const int cb = colB0 + (d0 * 16 + hi * 8) * 2;
;         const bf16x8 b0 = *reinterpret_cast<const bf16x8*>(Ks + KSWZ(r32, cb));
;         const bf16x8 b1 = *reinterpret_cast<const bf16x8*>(Ks + KSWZ(32 + r32, cb));
;         p0 = __builtin_amdgcn_mfma_f32_32x32x16_bf16(b0, qr[d0], p0, 0, 0, 0);
.Lsym_nostage_s3:
	s_waitcnt lgkmcnt(14)
	v_mfma_f32_32x32x16_bf16 v[48:63], v[128:131], v[144:147], v[48:63]
	ds_read_b64_tr_b16 v[144:145], v252 offset:53248
	ds_read_b64_tr_b16 v[146:147], v252 offset:55296
	v_exp_f32_e32 v120, v120
	v_exp_f32_e32 v121, v121
	v_exp_f32_e32 v122, v122
	s_waitcnt lgkmcnt(14)
	v_mfma_f32_32x32x16_bf16 v[32:47], v[128:131], v[148:151], v[32:47]
	ds_read_b64_tr_b16 v[148:149], v252 offset:53760
	ds_read_b64_tr_b16 v[150:151], v252 offset:55808
	v_exp_f32_e32 v123, v123
	v_add_f32_e32 v182, v120, v182
	v_add_f32_e32 v182, v121, v182
	v_cvt_pk_bf16_f32 v132, v120, v121
	v_exp_f32_e32 v124, v124
	s_waitcnt lgkmcnt(14)
	v_mfma_f32_32x32x16_bf16 v[16:31], v[128:131], v[152:155], v[16:31]
	ds_read_b64_tr_b16 v[152:153], v252 offset:54272
	ds_read_b64_tr_b16 v[154:155], v252 offset:56320
	v_exp_f32_e32 v125, v125
	v_add_f32_e32 v182, v122, v182
	v_add_f32_e32 v182, v123, v182
	v_cvt_pk_bf16_f32 v133, v122, v123
	s_waitcnt lgkmcnt(14)
	v_mfma_f32_32x32x16_bf16 v[0:15], v[128:131], v[156:159], v[0:15]
	ds_read_b64_tr_b16 v[156:157], v252 offset:54784
	ds_read_b64_tr_b16 v[158:159], v252 offset:56832
	v_exp_f32_e32 v126, v126
	v_exp_f32_e32 v127, v127
	v_add_f32_e32 v182, v124, v182
	v_add_f32_e32 v182, v125, v182
	s_waitcnt lgkmcnt(15)
	v_mfma_f32_32x32x16_bf16 v[80:95], v[192:195], v[172:175], v[80:95]
	v_cvt_pk_bf16_f32 v134, v124, v125
	v_cvt_pk_bf16_f32 v135, v126, v127
	v_add_f32_e32 v182, v126, v182
	v_add_f32_e32 v182, v127, v182
	v_exp_f32_e32 v96, v96
	s_waitcnt lgkmcnt(6)
	v_mfma_f32_32x32x16_bf16 v[48:63], v[132:135], v[144:147], v[48:63]
	ds_read_b64_tr_b16 v[144:145], v252 offset:57344
	ds_read_b64_tr_b16 v[146:147], v252 offset:59392
	v_exp_f32_e32 v97, v97
	v_exp_f32_e32 v98, v98
	v_exp_f32_e32 v99, v99
	v_add_f32_e32 v182, v96, v182
	v_mfma_f32_32x32x16_bf16 v[64:79], v[196:199], v[172:175], v[64:79]
	v_add_f32_e32 v182, v97, v182
	v_cvt_pk_bf16_f32 v136, v96, v97
	v_exp_f32_e32 v100, v100
	v_exp_f32_e32 v101, v101
	s_waitcnt lgkmcnt(6)
	v_mfma_f32_32x32x16_bf16 v[32:47], v[132:135], v[148:151], v[32:47]
	ds_read_b64_tr_b16 v[148:149], v252 offset:57856
	ds_read_b64_tr_b16 v[150:151], v252 offset:59904
	v_add_f32_e32 v182, v98, v182
	v_add_f32_e32 v182, v99, v182
	v_cvt_pk_bf16_f32 v137, v98, v99
	v_exp_f32_e32 v102, v102
	v_mfma_f32_32x32x16_bf16 v[80:95], v[200:203], v[168:171], v[80:95]
	v_exp_f32_e32 v103, v103
	v_add_f32_e32 v182, v100, v182
	v_add_f32_e32 v182, v101, v182
	v_cvt_pk_bf16_f32 v138, v100, v101
	v_cvt_pk_bf16_f32 v139, v102, v103
	v_add_f32_e32 v182, v102, v182
	s_waitcnt lgkmcnt(6)
	v_mfma_f32_32x32x16_bf16 v[16:31], v[132:135], v[152:155], v[16:31]
	ds_read_b64_tr_b16 v[152:153], v252 offset:58368
	ds_read_b64_tr_b16 v[154:155], v252 offset:60416
	v_add_f32_e32 v182, v103, v182
	v_exp_f32_e32 v104, v104
	v_exp_f32_e32 v105, v105
	v_exp_f32_e32 v106, v106
	v_mfma_f32_32x32x16_bf16 v[64:79], v[204:207], v[168:171], v[64:79]
	v_exp_f32_e32 v107, v107
	v_add_f32_e32 v182, v104, v182
	v_add_f32_e32 v182, v105, v182
	v_cvt_pk_bf16_f32 v140, v104, v105
	s_waitcnt lgkmcnt(6)
	v_mfma_f32_32x32x16_bf16 v[0:15], v[132:135], v[156:159], v[0:15]
	ds_read_b64_tr_b16 v[156:157], v252 offset:58880
	ds_read_b64_tr_b16 v[158:159], v252 offset:60928
	v_exp_f32_e32 v108, v108
	v_exp_f32_e32 v109, v109
	v_add_f32_e32 v182, v106, v182
	v_add_f32_e32 v182, v107, v182
	v_mfma_f32_32x32x16_bf16 v[80:95], v[208:211], v[164:167], v[80:95]
	v_cvt_pk_bf16_f32 v141, v106, v107
	v_exp_f32_e32 v110, v110
	v_exp_f32_e32 v111, v111
	v_add_f32_e32 v182, v108, v182
	v_mfma_f32_32x32x16_bf16 v[64:79], v[212:215], v[164:167], v[64:79]
	v_add_f32_e32 v182, v109, v182
	v_cvt_pk_bf16_f32 v142, v108, v109
	v_cvt_pk_bf16_f32 v143, v110, v111
	v_add_f32_e32 v182, v110, v182
	v_add_f32_e32 v182, v111, v182
	s_cmp_lt_i32 s55, 0
	s_cselect_b32 s100, -1.0, 1.0
	v_mul_f32_e32 v185, s100, v186
	v_mfma_f32_32x32x16_bf16 v[80:95], v[216:219], v[160:163], v[80:95]
	v_fma_f32 v187, -v185, v183, s16
	v_fmamk_f32 v112, v185, 0x00000000, v187
	v_fmamk_f32 v113, v185, 0x3f800000, v187
	v_fmamk_f32 v114, v185, 0x40000000, v187
	v_fmamk_f32 v115, v185, 0x40400000, v187
	v_fmamk_f32 v116, v185, 0x41000000, v187
	v_mfma_f32_32x32x16_bf16 v[64:79], v[220:223], v[160:163], v[64:79]
	v_fmamk_f32 v117, v185, 0x41100000, v187
	v_fmamk_f32 v118, v185, 0x41200000, v187
	v_fmamk_f32 v119, v185, 0x41300000, v187
	v_fmamk_f32 v120, v185, 0x41800000, v187
	v_fmamk_f32 v121, v185, 0x41880000, v187
	v_fmamk_f32 v122, v185, 0x41900000, v187
	s_waitcnt lgkmcnt(6)
	v_mfma_f32_32x32x16_bf16 v[48:63], v[136:139], v[144:147], v[48:63]
	ds_read_b64_tr_b16 v[144:145], v252 offset:61440
	ds_read_b64_tr_b16 v[146:147], v252 offset:63488
	v_fmamk_f32 v123, v185, 0x41980000, v187
	v_fmamk_f32 v124, v185, 0x41c00000, v187
	v_fmamk_f32 v125, v185, 0x41c80000, v187
	v_fmamk_f32 v126, v185, 0x41d00000, v187
	v_fmamk_f32 v127, v185, 0x41d80000, v187
	v_fmamk_f32 v96, v185, 0x42000000, v187
	s_waitcnt lgkmcnt(6)
; template <int KS> __device__ __forceinline__ void pv_ks(f32x16* o, int vb, bf16x8 pa) {
;     const s16x4 l0 = tr_read<v_rd_off(0, KS, 0)>(vb), h0 = tr_read<v_rd_off(0, KS, 1)>(vb), l1 = tr_read<v_rd_off(1, KS, 0)>(vb), h1 = tr_read<v_rd_off(1, KS, 1)>(vb);
;     const s16x4 l2 = tr_read<v_rd_off(2, KS, 0)>(vb), h2 = tr_read<v_rd_off(2, KS, 1)>(vb), l3 = tr_read<v_rd_off(3, KS, 0)>(vb), h3 = tr_read<v_rd_off(3, KS, 1)>(vb);
;     ...
;     asm volatile("s_waitcnt lgkmcnt(6)" ::: "memory"); SBAR();
;     o[0] = __builtin_amdgcn_mfma_f32_32x32x16_bf16(pa, PK(l0, h0), o[0], 0, 0, 0);
;     asm volatile("s_waitcnt lgkmcnt(4)" ::: "memory"); SBAR();
;     o[1] = __builtin_amdgcn_mfma_f32_32x32x16_bf16(pa, PK(l1, h1), o[1], 0, 0, 0);
;     asm volatile("s_waitcnt lgkmcnt(2)" ::: "memory"); SBAR();
;     o[2] = __builtin_amdgcn_mfma_f32_32x32x16_bf16(pa, PK(l2, h2), o[2], 0, 0, 0);
;     asm volatile("s_waitcnt lgkmcnt(0)" ::: "memory"); SBAR();
;     o[3] = __builtin_amdgcn_mfma_f32_32x32x16_bf16(pa, PK(l3, h3), o[3], 0, 0, 0);
;     ...
; }
; __device__ __forceinline__ void pv_d0(f32x16* o, int vb, bf16x8 pa0, bf16x8 pa1, bf16x8 pa2, bf16x8 pa3) {
;     __builtin_amdgcn_s_setprio(1);
;     pv_ks<0>(o, vb, pa0); pv_ks<1>(o, vb, pa1); pv_ks<2>(o, vb, pa2); pv_ks<3>(o, vb, pa3);
;     __builtin_amdgcn_s_setprio(0);
; }
; __device__ __forceinline__ void exp_half(f32x16& p) {
; #pragma unroll
;     for (int r = 0; r < 16; ++r) p[r] = __builtin_amdgcn_exp2f(p[r]);
; }
; __device__ __forceinline__ void pack_p(const f32x16& p0, const f32x16& p1, float& l_reg, bf16x8& pa0, bf16x8& pa1, bf16x8& pa2, bf16x8& pa3) {
;     float ps = 0;
; #pragma unroll
;     for (int r = 0; r < 16; ++r) ps += p0[r];
; #pragma unroll
;     for (int r = 0; r < 16; ++r) ps += p1[r];
;     l_reg += ps;
;     ...
;     PK4(p0, 0, pa0); PK4(p0, 8, pa1); PK4(p1, 0, pa2); PK4(p1, 8, pa3);
;     ...
; }
; template <int ND0> __device__ __forceinline__ void qkt(f32x16& p0, f32x16& p1, const char* Ks, const bf16x8* qr, int r32, int hi, int colB0) {
; #pragma unroll
;     for (int d0 = 0; d0 < ND0; ++d0) { const int cb = colB0 + (d0 * 16 + hi * 8) * 2;
;         const bf16x8 b0 = *reinterpret_cast<const bf16x8*>(Ks + KSWZ(r32, cb));
;         const bf16x8 b1 = *reinterpret_cast<const bf16x8*>(Ks + KSWZ(32 + r32, cb));
;         p0 = __builtin_amdgcn_mfma_f32_32x32x16_bf16(b0, qr[d0], p0, 0, 0, 0);
	v_mfma_f32_32x32x16_bf16 v[32:47], v[136:139], v[148:151], v[32:47]
	ds_read_b64_tr_b16 v[148:149], v252 offset:61952
	ds_read_b64_tr_b16 v[150:151], v252 offset:64000
	v_fmamk_f32 v97, v185, 0x42040000, v187
	v_fmamk_f32 v98, v185, 0x42080000, v187
	v_fmamk_f32 v99, v185, 0x420c0000, v187
	v_fmamk_f32 v100, v185, 0x42200000, v187
	v_fmamk_f32 v101, v185, 0x42240000, v187
	v_fmamk_f32 v102, v185, 0x42280000, v187
	s_waitcnt lgkmcnt(6)
	v_mfma_f32_32x32x16_bf16 v[16:31], v[136:139], v[152:155], v[16:31]
	ds_read_b64_tr_b16 v[152:153], v252 offset:62464
	ds_read_b64_tr_b16 v[154:155], v252 offset:64512
	v_fmamk_f32 v103, v185, 0x422c0000, v187
	v_fmamk_f32 v104, v185, 0x42400000, v187
	v_fmamk_f32 v105, v185, 0x42440000, v187
	v_fmamk_f32 v106, v185, 0x42480000, v187
	v_fmamk_f32 v107, v185, 0x424c0000, v187
	v_fmamk_f32 v108, v185, 0x42600000, v187
	s_waitcnt lgkmcnt(6)
	v_mfma_f32_32x32x16_bf16 v[0:15], v[136:139], v[156:159], v[0:15]
	ds_read_b64_tr_b16 v[156:157], v252 offset:62976
	ds_read_b64_tr_b16 v[158:159], v252 offset:65024
	v_fmamk_f32 v109, v185, 0x42640000, v187
	v_fmamk_f32 v110, v185, 0x42680000, v187
	v_fmamk_f32 v111, v185, 0x426c0000, v187
	v_exp_f32_e32 v80, v80
	v_exp_f32_e32 v81, v81
	s_waitcnt lgkmcnt(6)
	v_mfma_f32_32x32x16_bf16 v[48:63], v[140:143], v[144:147], v[48:63]
	ds_read_b64_tr_b16 v[144:145], v252 offset:0
	ds_read_b64_tr_b16 v[146:147], v252 offset:2048
	v_exp_f32_e32 v82, v82
	v_exp_f32_e32 v83, v83
	v_add_f32_e32 v182, v80, v182
	v_add_f32_e32 v182, v81, v182
	s_waitcnt lgkmcnt(6)
	v_mfma_f32_32x32x16_bf16 v[32:47], v[140:143], v[148:151], v[32:47]
	ds_read_b64_tr_b16 v[148:149], v252 offset:512
	ds_read_b64_tr_b16 v[150:151], v252 offset:2560
	v_cvt_pk_bf16_f32 v128, v80, v81
	v_exp_f32_e32 v84, v84
	v_exp_f32_e32 v85, v85
	v_add_f32_e32 v182, v82, v182
	s_waitcnt lgkmcnt(6)
	v_mfma_f32_32x32x16_bf16 v[16:31], v[140:143], v[152:155], v[16:31]
	ds_read_b64_tr_b16 v[152:153], v252 offset:1024
	ds_read_b64_tr_b16 v[154:155], v252 offset:3072
	v_add_f32_e32 v182, v83, v182
	v_cvt_pk_bf16_f32 v129, v82, v83
	v_exp_f32_e32 v86, v86
	v_exp_f32_e32 v87, v87
	s_waitcnt lgkmcnt(6)
	v_mfma_f32_32x32x16_bf16 v[0:15], v[140:143], v[156:159], v[0:15]
	ds_read_b64_tr_b16 v[156:157], v252 offset:1536
	ds_read_b64_tr_b16 v[158:159], v252 offset:3584
	v_add_f32_e32 v182, v84, v182
	v_add_f32_e32 v182, v85, v182
	v_cvt_pk_bf16_f32 v130, v84, v85
	v_cvt_pk_bf16_f32 v131, v86, v87
	v_add_f32_e32 v182, v86, v182
	v_add_f32_e32 v182, v87, v182
	s_add_i32 s100, s55, 62
	s_cmp_lt_u32 s100, 93
	s_cbranch_scc0 .Lsym_nodiag_s3
	v_add_f32_e32 v190, 0x00000000, v183
	v_add_f32_e32 v191, 0xc2000000, v183
	v_fma_f32 v112, |v190|, v186, s16
	v_fma_f32 v96, |v191|, v186, s16
	v_add_f32_e32 v190, 0xbf800000, v183
	v_add_f32_e32 v191, 0xc2040000, v183
	v_fma_f32 v113, |v190|, v186, s16
	v_fma_f32 v97, |v191|, v186, s16
	v_add_f32_e32 v190, 0xc0000000, v183
	v_add_f32_e32 v191, 0xc2080000, v183
	v_fma_f32 v114, |v190|, v186, s16
	v_fma_f32 v98, |v191|, v186, s16
	v_add_f32_e32 v190, 0xc0400000, v183
	v_add_f32_e32 v191, 0xc20c0000, v183
	v_fma_f32 v115, |v190|, v186, s16
	v_fma_f32 v99, |v191|, v186, s16
	v_add_f32_e32 v190, 0xc1000000, v183
	v_add_f32_e32 v191, 0xc2200000, v183
	v_fma_f32 v116, |v190|, v186, s16
	v_fma_f32 v100, |v191|, v186, s16
	v_add_f32_e32 v190, 0xc1100000, v183
	v_add_f32_e32 v191, 0xc2240000, v183
	v_fma_f32 v117, |v190|, v186, s16
	v_fma_f32 v101, |v191|, v186, s16
	v_add_f32_e32 v190, 0xc1200000, v183
	v_add_f32_e32 v191, 0xc2280000, v183
	v_fma_f32 v118, |v190|, v186, s16
	v_fma_f32 v102, |v191|, v186, s16
	v_add_f32_e32 v190, 0xc1300000, v183
	v_add_f32_e32 v191, 0xc22c0000, v183
	v_fma_f32 v119, |v190|, v186, s16
	v_fma_f32 v103, |v191|, v186, s16
	v_add_f32_e32 v190, 0xc1800000, v183
	v_add_f32_e32 v191, 0xc2400000, v183
	v_fma_f32 v120, |v190|, v186, s16
	v_fma_f32 v104, |v191|, v186, s16
	v_add_f32_e32 v190, 0xc1880000, v183
	v_add_f32_e32 v191, 0xc2440000, v183
	v_fma_f32 v121, |v190|, v186, s16
	v_fma_f32 v105, |v191|, v186, s16
	v_add_f32_e32 v190, 0xc1900000, v183
	v_add_f32_e32 v191, 0xc2480000, v183
	v_fma_f32 v122, |v190|, v186, s16
	v_fma_f32 v106, |v191|, v186, s16
	v_add_f32_e32 v190, 0xc1980000, v183
	v_add_f32_e32 v191, 0xc24c0000, v183
	v_fma_f32 v123, |v190|, v186, s16
	v_fma_f32 v107, |v191|, v186, s16
	v_add_f32_e32 v190, 0xc1c00000, v183
	v_add_f32_e32 v191, 0xc2600000, v183
	v_fma_f32 v124, |v190|, v186, s16
	v_fma_f32 v108, |v191|, v186, s16
	v_add_f32_e32 v190, 0xc1c80000, v183
	v_add_f32_e32 v191, 0xc2640000, v183
	v_fma_f32 v125, |v190|, v186, s16
	v_fma_f32 v109, |v191|, v186, s16
	v_add_f32_e32 v190, 0xc1d00000, v183
	v_add_f32_e32 v191, 0xc2680000, v183
	v_fma_f32 v126, |v190|, v186, s16
	v_fma_f32 v110, |v191|, v186, s16
	v_add_f32_e32 v190, 0xc1d80000, v183
	v_add_f32_e32 v191, 0xc26c0000, v183
	v_fma_f32 v127, |v190|, v186, s16
	v_fma_f32 v111, |v191|, v186, s16
